# speedup vs baseline: 1.0110x; 1.0110x over previous
; template <bool WIDE>
; __device__ __forceinline__ void outproj_tile(const Params& P, int l, int mt, int nt, char* smem) {
;     ...
; #pragma unroll 4
;     for (int q = 0; q < 16; ++q) {
;       float4 y = *(const float4*)(cs + r * CSTR + half * 64 + q * 4);
;       float4 xv = *(const float4*)(xin + q * 4);
;       float4 g = *(const float4*)(g1 + q * 4);
;       float4 o = make_float4(xv.x + g.x * y.x, xv.y + g.y * y.y, xv.z + g.z * y.z, xv.w + g.w * y.w);
;       *(float4*)(xo + q * 4) = o;
;     }
.LBB0_716:
	v_lshl_add_u64 v[144:145], v[138:139], 0, s[18:19]
	v_add_co_u32_e32 v160, vcc, 0x11f42000, v144
	v_lshl_add_u64 v[148:149], v[132:133], 0, s[18:19]
	s_nop 0
	v_addc_co_u32_e32 v161, vcc, 0, v145, vcc
	global_load_dwordx4 v[140:143], v[148:149], off
	global_load_dwordx4 v[144:147], v[160:161], off
	global_load_dwordx4 v[156:159], v[148:149], off offset:16
	global_load_dwordx4 v[164:167], v[160:161], off offset:16
	global_load_dwordx4 v[172:175], v[148:149], off offset:32
	global_load_dwordx4 v[176:179], v[160:161], off offset:32
	global_load_dwordx4 v[184:187], v[148:149], off offset:48
	global_load_dwordx4 v[188:191], v[160:161], off offset:48
	global_load_dwordx4 v[196:199], v[148:149], off offset:64
	global_load_dwordx4 v[200:203], v[160:161], off offset:64
	global_load_dwordx4 v[208:211], v[148:149], off offset:80
	global_load_dwordx4 v[212:215], v[160:161], off offset:80
	global_load_dwordx4 v[224:227], v[148:149], off offset:96
	global_load_dwordx4 v[228:231], v[160:161], off offset:96
	global_load_dwordx4 v[236:239], v[148:149], off offset:112
	global_load_dwordx4 v[240:243], v[160:161], off offset:112
	ds_read_b128 v[152:155], v130
	ds_read_b128 v[168:171], v130 offset:16
	ds_read_b128 v[180:183], v130 offset:32
	ds_read_b128 v[192:195], v130 offset:48
	ds_read_b128 v[204:207], v130 offset:64
	ds_read_b128 v[216:219], v130 offset:80
	ds_read_b128 v[232:235], v130 offset:96
	ds_read_b128 v[244:247], v130 offset:112
	v_add_u32_e32 v130, 0x80, v130
	v_lshl_add_u64 v[162:163], v[136:137], 0, s[18:19]
	s_add_u32 s18, s18, 0x80
	s_addc_u32 s19, s19, 0
	s_cmpk_eq_i32 s18, 0x100
	s_waitcnt vmcnt(14) lgkmcnt(7)
	v_pk_fma_f32 v[140:141], v[152:153], v[144:145], v[140:141]
	v_pk_fma_f32 v[142:143], v[154:155], v[146:147], v[142:143]
	global_store_dwordx4 v[162:163], v[140:143], off
	s_waitcnt vmcnt(13) lgkmcnt(6)
	v_pk_fma_f32 v[156:157], v[168:169], v[164:165], v[156:157]
	v_pk_fma_f32 v[158:159], v[170:171], v[166:167], v[158:159]
	global_store_dwordx4 v[162:163], v[156:159], off offset:16
	s_waitcnt vmcnt(12) lgkmcnt(5)
	v_pk_fma_f32 v[172:173], v[180:181], v[176:177], v[172:173]
	v_pk_fma_f32 v[174:175], v[182:183], v[178:179], v[174:175]
	global_store_dwordx4 v[162:163], v[172:175], off offset:32
	s_waitcnt vmcnt(11) lgkmcnt(4)
	v_pk_fma_f32 v[184:185], v[192:193], v[188:189], v[184:185]
	v_pk_fma_f32 v[186:187], v[194:195], v[190:191], v[186:187]
	global_store_dwordx4 v[162:163], v[184:187], off offset:48
	s_waitcnt vmcnt(10) lgkmcnt(3)
	v_pk_fma_f32 v[196:197], v[204:205], v[200:201], v[196:197]
	v_pk_fma_f32 v[198:199], v[206:207], v[202:203], v[198:199]
	global_store_dwordx4 v[162:163], v[196:199], off offset:64
	s_waitcnt vmcnt(9) lgkmcnt(2)
	v_pk_fma_f32 v[208:209], v[216:217], v[212:213], v[208:209]
	v_pk_fma_f32 v[210:211], v[218:219], v[214:215], v[210:211]
	global_store_dwordx4 v[162:163], v[208:211], off offset:80
	s_waitcnt vmcnt(8) lgkmcnt(1)
	v_pk_fma_f32 v[224:225], v[232:233], v[228:229], v[224:225]
	v_pk_fma_f32 v[226:227], v[234:235], v[230:231], v[226:227]
	global_store_dwordx4 v[162:163], v[224:227], off offset:96
	s_waitcnt vmcnt(7) lgkmcnt(0)
	v_pk_fma_f32 v[236:237], v[244:245], v[240:241], v[236:237]
	v_pk_fma_f32 v[238:239], v[246:247], v[242:243], v[238:239]
	global_store_dwordx4 v[162:163], v[236:239], off offset:112
	s_cbranch_scc0 .LBB0_716
	s_mov_b32 s15, 1
	s_mov_b64 s[18:19], 0
	s_and_b64 vcc, exec, s[20:21]
	s_barrier
	s_cbranch_vccz .LBB0_709
	s_add_i32 s51, s51, s94
	s_cmpk_gt_i32 s51, 0x3ff
	s_cbranch_scc0 .LBB0_706

; template <bool WIDE>
; __device__ __forceinline__ void outproj_tile(const Params& P, int l, int mt, int nt, char* smem) {
;     ...
; #pragma unroll 4
;     for (int q = 0; q < 16; ++q) {
;       float4 y = *(const float4*)(cs + r * CSTR + half * 64 + q * 4);
;       float4 xv = *(const float4*)(xin + q * 4);
;       float4 g = *(const float4*)(g1 + q * 4);
;       float4 o = make_float4(xv.x + g.x * y.x, xv.y + g.y * y.y, xv.z + g.z * y.z, xv.w + g.w * y.w);
;       *(float4*)(xo + q * 4) = o;
;     }
.LBB0_1720:
	v_lshl_add_u64 v[148:149], v[138:139], 0, s[16:17]
	v_add_co_u32_e32 v162, vcc, s50, v148
	v_lshl_add_u64 v[160:161], v[132:133], 0, s[16:17]
	s_nop 0
	v_addc_co_u32_e32 v163, vcc, 0, v149, vcc
	global_load_dwordx4 v[144:147], v[160:161], off
	global_load_dwordx4 v[148:151], v[162:163], off
	global_load_dwordx4 v[140:143], v[160:161], off offset:16
	global_load_dwordx4 v[156:159], v[162:163], off offset:16
	global_load_dwordx4 v[168:171], v[160:161], off offset:32
	global_load_dwordx4 v[172:175], v[162:163], off offset:32
	global_load_dwordx4 v[180:183], v[160:161], off offset:48
	global_load_dwordx4 v[184:187], v[162:163], off offset:48
	global_load_dwordx4 v[192:195], v[160:161], off offset:64
	global_load_dwordx4 v[196:199], v[162:163], off offset:64
	global_load_dwordx4 v[204:207], v[160:161], off offset:80
	global_load_dwordx4 v[208:211], v[162:163], off offset:80
	global_load_dwordx4 v[216:219], v[160:161], off offset:96
	global_load_dwordx4 v[224:227], v[162:163], off offset:96
	global_load_dwordx4 v[232:235], v[160:161], off offset:112
	global_load_dwordx4 v[236:239], v[162:163], off offset:112
	ds_read_b128 v[152:155], v130
	ds_read_b128 v[164:167], v130 offset:16
	ds_read_b128 v[176:179], v130 offset:32
	ds_read_b128 v[188:191], v130 offset:48
	ds_read_b128 v[200:203], v130 offset:64
	ds_read_b128 v[212:215], v130 offset:80
	ds_read_b128 v[228:231], v130 offset:96
	ds_read_b128 v[240:243], v130 offset:112
	v_add_u32_e32 v130, 0x80, v130
	s_add_u32 s16, s16, 0x80
	s_addc_u32 s17, s17, 0
	s_cmpk_eq_i32 s16, 0x100
	s_waitcnt vmcnt(14) lgkmcnt(7)
	v_pk_fma_f32 v[144:145], v[152:153], v[148:149], v[144:145]
	v_pk_fma_f32 v[146:147], v[154:155], v[150:151], v[146:147]
	global_store_dwordx4 v[160:161], v[144:147], off
	s_waitcnt vmcnt(13) lgkmcnt(6)
	v_pk_fma_f32 v[140:141], v[164:165], v[156:157], v[140:141]
	v_pk_fma_f32 v[142:143], v[166:167], v[158:159], v[142:143]
	global_store_dwordx4 v[160:161], v[140:143], off offset:16
	s_waitcnt vmcnt(12) lgkmcnt(5)
	v_pk_fma_f32 v[168:169], v[176:177], v[172:173], v[168:169]
	v_pk_fma_f32 v[170:171], v[178:179], v[174:175], v[170:171]
	global_store_dwordx4 v[160:161], v[168:171], off offset:32
	s_waitcnt vmcnt(11) lgkmcnt(4)
	v_pk_fma_f32 v[180:181], v[188:189], v[184:185], v[180:181]
	v_pk_fma_f32 v[182:183], v[190:191], v[186:187], v[182:183]
	global_store_dwordx4 v[160:161], v[180:183], off offset:48
	s_waitcnt vmcnt(10) lgkmcnt(3)
	v_pk_fma_f32 v[192:193], v[200:201], v[196:197], v[192:193]
	v_pk_fma_f32 v[194:195], v[202:203], v[198:199], v[194:195]
	global_store_dwordx4 v[160:161], v[192:195], off offset:64
	s_waitcnt vmcnt(9) lgkmcnt(2)
	v_pk_fma_f32 v[204:205], v[212:213], v[208:209], v[204:205]
	v_pk_fma_f32 v[206:207], v[214:215], v[210:211], v[206:207]
	global_store_dwordx4 v[160:161], v[204:207], off offset:80
	s_waitcnt vmcnt(8) lgkmcnt(1)
	v_pk_fma_f32 v[216:217], v[228:229], v[224:225], v[216:217]
	v_pk_fma_f32 v[218:219], v[230:231], v[226:227], v[218:219]
	global_store_dwordx4 v[160:161], v[216:219], off offset:96
	s_waitcnt vmcnt(7) lgkmcnt(0)
	v_pk_fma_f32 v[232:233], v[240:241], v[236:237], v[232:233]
	v_pk_fma_f32 v[234:235], v[242:243], v[238:239], v[234:235]
	global_store_dwordx4 v[160:161], v[232:235], off offset:112
	s_cbranch_scc0 .LBB0_1720
	s_mov_b32 s53, 1
	s_mov_b64 s[16:17], 0
	s_and_b64 vcc, exec, s[14:15]
	s_barrier
	s_cbranch_vccz .LBB0_1717
	s_add_i32 s51, s51, s94
	s_cmpk_lt_i32 s51, 0x400
	s_cbranch_scc1 .LBB0_1714
